# mLSTM chunk loop: wave-uniform branch test trimmed (two VALU ballot re-derivations replaced by one s_andn2), on top of the wave-7 priority version
# baseline (speedup 1.0000x reference)
; __device__ __forceinline__ void mlstm_unit(KArg P, int L, int b, int h, int vs, LAS unsigned char* lds) {
;     ...
;             if (w == 7 && ch + 1 < 64) gates(FL + ((ch + 1) & 1) * FL_GSZ);
;             if (ch + 1 < 64) stage_qk();
;         }
;         __syncthreads();
;         if (ch + 1 < 64) stage_kt_v(FL + ((ch + 1) & 1) * FL_GSZ);
.LBB0_550:
	s_andn2_b64 s[34:35], exec, s[44:45]
	s_andn2_b64 vcc, exec, s[44:45]
	s_cbranch_vccnz .LBB0_552

; #define LAS __attribute__((address_space(3)))
; __device__ __forceinline__ unsigned cvt_pk_bf16(float lo, float hi) { f32x2_t v = {lo, hi}; bf16x2_t b = __builtin_convertvector(v, bf16x2_t); return __builtin_bit_cast(unsigned, b); }
; __device__ __forceinline__ void mlstm_unit(KArg P, int L, int b, int h, int vs, LAS unsigned char* lds) {
;     ...
;         const float M63 = __int_as_float(__builtin_amdgcn_readlane(__float_as_int(Mx), 63)), blast = __int_as_float(__builtin_amdgcn_readlane(__float_as_int(bsum), 63));
;         gb[FL_A + lane] = a; gb[FL_MX + lane] = Mx; gb[FL_WIN + lane] = __expf(m_st - Mx); gb[FL_FLOOR + lane] = __expf(-(bsum + Mx)); { const float wst = __expf(a - M63); gb[FL_WST + lane] = wst; ((LAS bf16*)(gb + FL_WSTB))[lane] = (bf16)(cvt_pk_bf16(wst, 0.f) & 0xffffu); }
;         if (lane == 0) gb[FL_SC] = __expf(m_st - M63);
;         m_st = blast + M63;
.LBB0_560:
	s_or_b64 exec, exec, s[34:35]
	v_mov_b32_e32 v64, s43
	v_add_f32_e32 v97, s41, v64
	s_andn2_b64 s[34:35], exec, s[44:45]
	s_andn2_b64 vcc, exec, s[44:45]
	s_cbranch_vccz .LBB0_551
	s_branch .LBB0_552
